# states tile prologue: the A_log load is issued together with the dt / dt_bias loads (one wait) instead of as a third serial round trip
# speedup vs baseline: 1.0068x; 1.0068x over previous
.LBB0_1272:
	v_mov_b32_e32 v121, v252
	s_waitcnt vmcnt(63) expcnt(7) lgkmcnt(15)
	s_barrier
	s_load_dwordx2 s[4:5], s[0:1], 0x60
	s_load_dwordx2 s[98:99], s[0:1], 0x68
	s_add_i32 s9, s18, 0xfffffdd9
	v_readfirstlane_b32 s8, v121
	v_and_b32_e32 v140, 63, v121
	s_ashr_i32 s30, s8, 6
	s_lshl_b32 s10, s9, 6
	v_or_b32_e32 v0, s10, v140
	s_ashr_i32 s31, s30, 31
	v_lshlrev_b64 v[2:3], 5, v[0:1]
	s_lshl_b64 s[2:3], s[30:31], 2
	v_lshl_add_u64 v[2:3], s[12:13], 0, v[2:3]
	s_waitcnt lgkmcnt(0)
	s_add_u32 s4, s4, s2
	v_lshl_add_u64 v[2:3], v[2:3], 0, s[2:3]
	s_addc_u32 s5, s5, s3
	global_load_dword v0, v[2:3], off
	s_nop 0
	global_load_dword v2, v1, s[4:5]
	s_add_u32 s98, s98, s2
	s_addc_u32 s99, s99, s3
	global_load_dword v250, v1, s[98:99]
	s_mov_b32 s4, 0x41a00000
	s_waitcnt vmcnt(0)
	v_add_f32_e32 v0, v0, v2
	v_cmp_nlt_f32_e32 vcc, s4, v0
	s_and_saveexec_b64 s[4:5], vcc
	s_cbranch_execz .LBB0_1274
	v_mul_f32_e32 v2, 0x3fb8aa3b, v0
	v_rndne_f32_e32 v3, v2
	s_mov_b32 s6, 0x3fb8aa3b
	v_sub_f32_e32 v4, v2, v3
	v_fma_f32 v2, v0, s6, -v2
	v_fmac_f32_e32 v2, 0x32a5705f, v0
	v_add_f32_e32 v2, v4, v2
	v_cvt_i32_f32_e32 v3, v3
	v_exp_f32_e32 v2, v2
	s_mov_b32 s6, 0xc2ce8ed0
	v_cmp_ngt_f32_e32 vcc, s6, v0
	s_mov_b32 s6, 0x3f2aaaab
	v_ldexp_f32 v2, v2, v3
	v_cndmask_b32_e32 v2, 0, v2, vcc
	v_cmp_nlt_f32_e32 vcc, s80, v0
	s_nop 1
	v_cndmask_b32_e32 v0, v183, v2, vcc
	v_add_f32_e32 v4, 1.0, v0
	v_add_f32_e32 v2, -1.0, v4
	v_sub_f32_e32 v3, v2, v4
	v_add_f32_e32 v3, 1.0, v3
	v_sub_f32_e32 v2, v0, v2
	v_add_f32_e32 v5, v2, v3
	v_frexp_mant_f32_e32 v6, v4
	v_cvt_f64_f32_e32 v[2:3], v4
	v_frexp_exp_i32_f64_e32 v2, v[2:3]
	v_cmp_gt_f32_e32 vcc, s6, v6
	s_mov_b32 s6, 0x3f317218
	s_nop 0
	v_subbrev_co_u32_e32 v10, vcc, 0, v2, vcc
	v_sub_u32_e32 v2, 0, v10
	v_ldexp_f32 v3, v4, v2
	v_add_f32_e32 v4, -1.0, v3
	v_add_f32_e32 v6, 1.0, v3
	v_ldexp_f32 v2, v5, v2
	v_add_f32_e32 v5, 1.0, v4
	v_add_f32_e32 v7, -1.0, v6
	v_sub_f32_e32 v5, v3, v5
	v_sub_f32_e32 v3, v3, v7
	v_add_f32_e32 v5, v2, v5
	v_add_f32_e32 v2, v2, v3
	v_add_f32_e32 v11, v6, v2
	v_rcp_f32_e32 v13, v11
	v_sub_f32_e32 v3, v6, v11
	v_add_f32_e32 v12, v2, v3
	v_add_f32_e32 v3, v4, v5
	v_mul_f32_e32 v15, v3, v13
	v_sub_f32_e32 v2, v4, v3
	v_mul_f32_e32 v4, v11, v15
	v_fma_f32 v6, v15, v11, -v4
	v_fmac_f32_e32 v6, v15, v12
	v_add_f32_e32 v14, v5, v2
	v_add_f32_e32 v2, v4, v6
	v_sub_f32_e32 v5, v3, v2
	v_pk_add_f32 v[8:9], v[2:3], v[4:5] neg_lo:[0,1] neg_hi:[0,1]
	v_mov_b32_e32 v7, v2
	v_pk_add_f32 v[2:3], v[8:9], v[6:7] neg_lo:[0,1] neg_hi:[0,1]
	s_nop 0
	v_add_f32_e32 v3, v14, v3
	v_add_f32_e32 v2, v2, v3
	v_add_f32_e32 v3, v5, v2
	v_mul_f32_e32 v14, v13, v3
	v_mul_f32_e32 v4, v11, v14
	v_fma_f32 v6, v14, v11, -v4
	v_fmac_f32_e32 v6, v14, v12
	v_sub_f32_e32 v5, v5, v3
	v_add_f32_e32 v11, v2, v5
	v_add_f32_e32 v2, v4, v6
	v_sub_f32_e32 v5, v3, v2
	v_pk_add_f32 v[8:9], v[2:3], v[4:5] neg_lo:[0,1] neg_hi:[0,1]
	v_mov_b32_e32 v7, v2
	v_pk_add_f32 v[2:3], v[8:9], v[6:7] neg_lo:[0,1] neg_hi:[0,1]
	s_nop 0
	v_add_f32_e32 v3, v11, v3
	v_add_f32_e32 v2, v2, v3
	v_add_f32_e32 v3, v15, v14
	v_add_f32_e32 v2, v5, v2
	v_sub_f32_e32 v4, v3, v15
	v_mul_f32_e32 v2, v13, v2
	v_sub_f32_e32 v4, v14, v4
	v_add_f32_e32 v4, v4, v2
	v_add_f32_e32 v6, v3, v4
	v_mul_f32_e32 v7, v6, v6
	v_fmamk_f32 v2, v7, 0x3e9b6dac, v178
	v_fmaak_f32 v165, v7, v2, 0x3f2aaada
	v_cvt_f32_i32_e32 v2, v10
	v_sub_f32_e32 v3, v6, v3
	v_sub_f32_e32 v3, v4, v3
	v_ldexp_f32 v8, v3, 1
	v_mul_f32_e32 v3, v6, v7
	v_ldexp_f32 v5, v6, 1
	v_pk_mul_f32 v[6:7], v[2:3], v[164:165]
	s_nop 0
	v_fma_f32 v4, v2, s6, -v6
	v_fmac_f32_e32 v4, 0xb102e308, v2
	v_pk_add_f32 v[2:3], v[6:7], v[4:5]
	s_mov_b32 s6, 0x7f800000
	v_sub_f32_e32 v5, v3, v5
	v_sub_f32_e32 v5, v7, v5
	v_add_f32_e32 v9, v8, v5
	v_mov_b32_e32 v8, v6
	v_pk_add_f32 v[6:7], v[2:3], v[6:7] neg_lo:[0,1] neg_hi:[0,1]
	v_pk_add_f32 v[10:11], v[2:3], v[8:9]
	v_mov_b32_e32 v5, v2
	v_mov_b32_e32 v7, v11
	v_pk_add_f32 v[12:13], v[4:5], v[6:7] neg_lo:[0,1] neg_hi:[0,1]
	v_pk_add_f32 v[4:5], v[4:5], v[6:7]
	v_mov_b32_e32 v8, v9
	v_pk_add_f32 v[6:7], v[4:5], v[2:3] op_sel:[1,0] op_sel_hi:[0,1] neg_lo:[0,1] neg_hi:[0,1]
	v_pk_add_f32 v[14:15], v[10:11], v[6:7] op_sel_hi:[1,0] neg_lo:[0,1] neg_hi:[0,1]
	v_mov_b32_e32 v10, v11
	v_mov_b32_e32 v11, v5
	v_pk_mov_b32 v[6:7], v[2:3], v[6:7] op_sel:[1,0]
	v_mov_b32_e32 v9, v2
	v_pk_add_f32 v[6:7], v[10:11], v[6:7] neg_lo:[0,1] neg_hi:[0,1]
	v_mov_b32_e32 v14, v12
	v_pk_add_f32 v[2:3], v[8:9], v[6:7] neg_lo:[0,1] neg_hi:[0,1]
	v_mov_b32_e32 v13, v5
	v_pk_add_f32 v[6:7], v[14:15], v[2:3]
	v_cmp_neq_f32_e32 vcc, s6, v0
	v_pk_add_f32 v[8:9], v[6:7], v[6:7] op_sel:[0,1] op_sel_hi:[1,0]
	s_mov_b32 s6, 0x33800000
	v_pk_add_f32 v[4:5], v[4:5], v[8:9] op_sel:[1,0] op_sel_hi:[0,1]
	v_mov_b32_e32 v7, v4
	v_pk_add_f32 v[10:11], v[6:7], v[12:13] neg_lo:[0,1] neg_hi:[0,1]
	v_mov_b32_e32 v3, v8
	v_sub_f32_e32 v5, v6, v10
	v_pk_add_f32 v[2:3], v[2:3], v[10:11] neg_lo:[0,1] neg_hi:[0,1]
	v_sub_f32_e32 v5, v12, v5
	v_add_f32_e32 v2, v2, v5
	v_add_f32_e32 v2, v2, v3
	v_add_f32_e32 v2, v4, v2
	v_cndmask_b32_e32 v2, v183, v2, vcc
	v_cmp_lt_f32_e64 vcc, |v0|, s6
	s_nop 1
	v_cndmask_b32_e32 v0, v2, v0, vcc
.LBB0_1274:
	s_or_b64 exec, exec, s[4:5]
	v_mov_b32_e32 v2, v250
	s_mov_b32 s2, 0x3fb8aa3b
	v_mul_f32_e32 v3, 0x3fb8aa3b, v2
	v_fma_f32 v4, v2, s2, -v3
	v_rndne_f32_e32 v5, v3
	v_fmac_f32_e32 v4, 0x32a5705f, v2
	v_sub_f32_e32 v3, v3, v5
	v_add_f32_e32 v3, v3, v4
	v_exp_f32_e32 v3, v3
	v_cvt_i32_f32_e32 v4, v5
	s_mov_b32 s2, 0xc2ce8ed0
	v_cmp_ngt_f32_e32 vcc, s2, v2
	v_add_u32_e32 v5, -1, v179
	v_ldexp_f32 v3, v3, v4
	v_cndmask_b32_e32 v3, 0, v3, vcc
	v_cmp_nlt_f32_e32 vcc, s80, v2
	v_and_b32_e32 v4, 64, v179
	s_and_b32 s2, s8, 0x3fffffc0
	v_cndmask_b32_e32 v2, v183, v3, vcc
	v_cmp_lt_i32_e32 vcc, v5, v4
	v_mul_f32_e64 v3, v0, -v2
	s_nop 0
	v_cndmask_b32_e32 v5, v5, v179, vcc
	v_lshlrev_b32_e32 v5, 2, v5
	ds_bpermute_b32 v5, v5, v3
	v_cmp_eq_u32_e32 vcc, 0, v140
	s_waitcnt lgkmcnt(0)
	v_fma_f32 v2, v0, -v2, v5
	v_cndmask_b32_e32 v2, v2, v3, vcc
	v_add_u32_e32 v3, -2, v179
	v_cmp_lt_i32_e64 s[40:41], v3, v4
	s_nop 1
	v_cndmask_b32_e64 v3, v3, v179, s[40:41]
	v_lshlrev_b32_e32 v3, 2, v3
	ds_bpermute_b32 v3, v3, v2
	v_cmp_gt_u32_e64 s[40:41], 2, v140
	s_waitcnt lgkmcnt(0)
	v_add_f32_e32 v3, v2, v3
	v_cndmask_b32_e64 v2, v3, v2, s[40:41]
	v_add_u32_e32 v3, -4, v179
	v_cmp_lt_i32_e64 s[40:41], v3, v4
	s_nop 1
	v_cndmask_b32_e64 v3, v3, v179, s[40:41]
	v_lshlrev_b32_e32 v3, 2, v3
	ds_bpermute_b32 v3, v3, v2
	v_cmp_gt_u32_e64 s[40:41], 4, v140
	s_waitcnt lgkmcnt(0)
	v_add_f32_e32 v3, v2, v3
	v_cndmask_b32_e64 v2, v3, v2, s[40:41]
	v_add_u32_e32 v3, -8, v179
	v_cmp_lt_i32_e64 s[40:41], v3, v4
	s_nop 1
	v_cndmask_b32_e64 v3, v3, v179, s[40:41]
	v_lshlrev_b32_e32 v3, 2, v3
	ds_bpermute_b32 v3, v3, v2
	v_cmp_gt_u32_e64 s[40:41], 8, v140
	s_waitcnt lgkmcnt(0)
	v_add_f32_e32 v3, v2, v3
	v_cndmask_b32_e64 v2, v3, v2, s[40:41]
	v_add_u32_e32 v3, -16, v179
	v_cmp_lt_i32_e64 s[40:41], v3, v4
	s_nop 1
	v_cndmask_b32_e64 v3, v3, v179, s[40:41]
	v_lshlrev_b32_e32 v3, 2, v3
	ds_bpermute_b32 v3, v3, v2
	v_cmp_gt_u32_e64 s[40:41], 16, v140
	s_waitcnt lgkmcnt(0)
	v_add_f32_e32 v3, v2, v3
	v_cndmask_b32_e64 v2, v3, v2, s[40:41]
	v_subrev_u32_e32 v3, 32, v179
	v_cmp_lt_i32_e64 s[40:41], v3, v4
	s_nop 1
	v_cndmask_b32_e64 v3, v3, v179, s[40:41]
	v_lshlrev_b32_e32 v3, 2, v3
	ds_bpermute_b32 v3, v3, v2
	v_cmp_gt_u32_e64 s[40:41], 32, v140
	s_waitcnt lgkmcnt(0)
	v_add_f32_e32 v3, v2, v3
	v_cndmask_b32_e64 v2, v3, v2, s[40:41]
	v_or_b32_e32 v3, s2, v140
	v_lshl_add_u32 v3, v3, 2, 0
	v_add_u32_e32 v4, 0x20800, v3
	ds_write_b32 v4, v0
	v_add_u32_e32 v0, 0x21000, v3
	ds_write_b32 v0, v2
	v_lshl_or_b32 v0, v179, 2, v184
	ds_bpermute_b32 v0, v0, v2
	s_and_saveexec_b64 s[2:3], vcc
	s_cbranch_execz .LBB0_1276
	s_waitcnt lgkmcnt(0)
	v_mul_f32_e32 v2, 0x3fb8aa3b, v0
	v_rndne_f32_e32 v3, v2
	s_mov_b32 s4, 0x3fb8aa3b
	v_sub_f32_e32 v4, v2, v3
	v_fma_f32 v2, v0, s4, -v2
	v_fmac_f32_e32 v2, 0x32a5705f, v0
	v_add_f32_e32 v2, v4, v2
	v_cvt_i32_f32_e32 v3, v3
	v_exp_f32_e32 v2, v2
	s_mov_b32 s4, 0xc2ce8ed0
	v_cmp_ngt_f32_e32 vcc, s4, v0
	s_lshl_b32 s4, s9, 3
	s_add_i32 s4, s30, s4
	s_ashr_i32 s5, s4, 31
	v_ldexp_f32 v2, v2, v3
	s_lshl_b64 s[4:5], s[4:5], 2
	v_readlane_b32 s6, v254, 36
	v_cndmask_b32_e32 v2, 0, v2, vcc
	v_cmp_nlt_f32_e32 vcc, s80, v0
	s_add_u32 s4, s6, s4
	v_readlane_b32 s6, v254, 44
	v_cndmask_b32_e32 v0, v183, v2, vcc
	s_addc_u32 s5, s6, s5
	global_store_dword v1, v0, s[4:5]
